# E2 queue: next item index requested while the current item runs
# baseline (speedup 1.0000x reference)
.LBB0_656:
	s_and_b64 vcc, exec, s[0:1]
	s_cbranch_vccz .LBB0_773
	v_readlane_b32 s0, v254, 39
	v_readlane_b32 s1, v254, 40
	s_lshl_b64 s[0:1], s[0:1], 2
	s_add_u32 s0, s80, s0
	s_addc_u32 s1, s81, s1
	s_add_u32 s0, s0, 0x12cd8040
	s_addc_u32 s1, s1, 0
	s_and_saveexec_b64 s[14:15], s[92:93]
	v_mov_b32_e32 v251, 1
	s_nop 0
	global_atomic_add v250, v1, v251, s[0:1] sc0
	s_or_b64 exec, exec, s[14:15]
	s_branch .LBB0_661

.LBB0_661:
	s_and_saveexec_b64 s[14:15], s[92:93]
	s_cbranch_execz .LBB0_665
	s_waitcnt vmcnt(0)
	v_mov_b32_e32 v2, s69
	v_readfirstlane_b32 s3, v250
	ds_write_b32 v2, v250
	s_cmpk_gt_i32 s3, 0x36f
	s_cbranch_scc1 .LBB0_665
	v_mov_b32_e32 v251, 1
	s_nop 0
	global_atomic_add v250, v1, v251, s[0:1] sc0
.LBB0_665:
	s_or_b64 exec, exec, s[14:15]
	v_mov_b32_e32 v0, s69
	s_waitcnt vmcnt(1) lgkmcnt(0)
	s_barrier
	ds_read_b32 v0, v0
	s_movk_i32 s4, 0x36f
	s_mov_b64 s[14:15], -1
	s_waitcnt lgkmcnt(0)
	s_barrier
	v_cmp_lt_i32_e32 vcc, s4, v0
	v_readfirstlane_b32 s3, v0
	s_cbranch_vccnz .LBB0_660
	s_cmpk_gt_i32 s3, 0x6f
	s_cbranch_scc0 .LBB0_678
	s_add_i32 s4, s3, 0xfffffd90
	s_add_i32 s30, s3, 0xffffff90
	s_lshr_b32 s4, s4, 7
	s_add_i32 s4, s4, 16
	s_lshr_b32 s5, s30, 5
	s_cmpk_lt_u32 s30, 0x200
	s_cselect_b32 s6, 3, 5
	s_cselect_b32 s4, s5, s4
	s_cselect_b32 s7, 3, 15
	s_lshr_b32 s5, s30, s6
	s_lshr_b32 s6, s30, 1
	s_lshl_b32 s11, s4, 10
	s_and_b32 s6, s7, s6
	s_and_b32 s5, s5, 3
	s_and_b32 s10, s3, 1
	s_lshl_b32 s7, s4, 8
	s_addk_i32 s11, 0xd000
	s_cmp_lt_u32 s4, 16
	s_cselect_b32 s4, s7, s11
	s_lshl_b32 s6, s6, 6
	s_add_i32 s7, s4, s6
	s_cmp_eq_u32 s10, 0
	v_mov_b32_e32 v18, v202
	s_cselect_b64 vcc, -1, 0
	s_lshl_b32 s6, s5, 6
	s_lshl_b32 s4, s5, 7
	s_add_u32 s14, s74, s4
	v_and_b32_e32 v15, 63, v18
	v_ashrrev_i32_e32 v14, 6, v18
	v_lshlrev_b32_e32 v6, 3, v14
	s_addc_u32 s15, s75, 0
	v_lshlrev_b32_e32 v0, 1, v15
	v_lshl_add_u64 v[2:3], s[14:15], 0, v[0:1]
	v_sub_u32_e32 v0, 63, v6
	v_cndmask_b32_e32 v0, v0, v6, vcc
	v_add_u32_e32 v0, s7, v0
	v_mad_i64_i32 v[4:5], s[14:15], v0, s88, v[2:3]
	v_or_b32_e32 v0, 1, v6
	global_load_ushort v16, v[4:5], off offset:512
	v_sub_u32_e32 v4, 63, v0
	v_cndmask_b32_e32 v0, v4, v0, vcc
	v_add_u32_e32 v0, s7, v0
	v_mad_i64_i32 v[4:5], s[14:15], v0, s88, v[2:3]
	v_or_b32_e32 v0, 2, v6
	global_load_ushort v21, v[4:5], off offset:512
	v_sub_u32_e32 v4, 63, v0
	v_cndmask_b32_e32 v0, v4, v0, vcc
	v_add_u32_e32 v0, s7, v0
	v_mad_i64_i32 v[4:5], s[14:15], v0, s88, v[2:3]
	v_or_b32_e32 v0, 3, v6
	global_load_ushort v17, v[4:5], off offset:512
	v_sub_u32_e32 v4, 63, v0
	v_cndmask_b32_e32 v0, v4, v0, vcc
	v_add_u32_e32 v0, s7, v0
	v_mad_i64_i32 v[4:5], s[14:15], v0, s88, v[2:3]
	v_or_b32_e32 v0, 4, v6
	global_load_ushort v22, v[4:5], off offset:512
	v_sub_u32_e32 v4, 63, v0
	v_cndmask_b32_e32 v0, v4, v0, vcc
	v_add_u32_e32 v0, s7, v0
	v_mad_i64_i32 v[4:5], s[14:15], v0, s88, v[2:3]
	v_or_b32_e32 v0, 5, v6
	global_load_ushort v19, v[4:5], off offset:512
	v_sub_u32_e32 v4, 63, v0
	v_cndmask_b32_e32 v0, v4, v0, vcc
	v_add_u32_e32 v0, s7, v0
	v_mad_i64_i32 v[4:5], s[14:15], v0, s88, v[2:3]
	v_or_b32_e32 v0, 6, v6
	global_load_ushort v23, v[4:5], off offset:512
	v_sub_u32_e32 v4, 63, v0
	v_cndmask_b32_e32 v0, v4, v0, vcc
	v_add_u32_e32 v0, s7, v0
	v_mad_i64_i32 v[4:5], s[14:15], v0, s88, v[2:3]
	v_or_b32_e32 v0, 7, v6
	global_load_ushort v20, v[4:5], off offset:512
	v_sub_u32_e32 v4, 63, v0
	v_cndmask_b32_e32 v0, v4, v0, vcc
	v_add_u32_e32 v0, s7, v0
	v_mad_i64_i32 v[2:3], s[14:15], v0, s88, v[2:3]
	v_mov_b32_e32 v0, v202
	global_load_ushort v24, v[2:3], off offset:512
	s_lshl_b32 s24, s5, 8
	v_ashrrev_i32_e32 v6, 3, v0
	v_and_b32_e32 v11, -16, v6
	v_and_b32_e32 v10, 0x7f, v0
	v_sub_u32_e32 v0, 63, v11
	v_sub_u32_e32 v2, 62, v11
	v_or_b32_e32 v3, 1, v11
	v_cndmask_b32_e32 v0, v0, v11, vcc
	v_cndmask_b32_e32 v2, v2, v3, vcc
	v_add_u32_e32 v0, s7, v0
	v_add_u32_e32 v7, s7, v2
	v_mov_b64_e32 v[2:3], s[74:75]
	v_mad_i64_i32 v[4:5], s[14:15], v0, s88, v[2:3]
	s_mov_b32 s25, s31
	v_lshl_add_u64 v[4:5], v[4:5], 0, s[24:25]
	v_lshlrev_b32_e32 v0, 1, v10
	v_lshl_add_u64 v[4:5], v[4:5], 0, v[0:1]
	global_load_ushort v8, v[4:5], off offset:1024
	v_mad_i64_i32 v[4:5], s[14:15], v7, s88, v[2:3]
	v_lshl_add_u64 v[4:5], v[4:5], 0, s[24:25]
	v_lshl_add_u64 v[4:5], v[4:5], 0, v[0:1]
	global_load_ushort v7, v[4:5], off offset:1024
	v_or_b32_e32 v4, 2, v11
	v_sub_u32_e32 v5, 63, v4
	v_cndmask_b32_e32 v5, v5, v4, vcc
	v_sub_u32_e32 v4, 62, v4
	v_or_b32_e32 v9, 3, v11
	v_add_u32_e32 v5, s7, v5
	v_cndmask_b32_e32 v4, v4, v9, vcc
	v_add_u32_e32 v9, s7, v4
	v_mad_i64_i32 v[4:5], s[14:15], v5, s88, v[2:3]
	v_lshl_add_u64 v[4:5], v[4:5], 0, s[24:25]
	v_lshl_add_u64 v[4:5], v[4:5], 0, v[0:1]
	global_load_ushort v12, v[4:5], off offset:1024
	v_mad_i64_i32 v[4:5], s[14:15], v9, s88, v[2:3]
	v_lshl_add_u64 v[4:5], v[4:5], 0, s[24:25]
	v_lshl_add_u64 v[4:5], v[4:5], 0, v[0:1]
	global_load_ushort v9, v[4:5], off offset:1024
	v_or_b32_e32 v4, 4, v11
	v_sub_u32_e32 v5, 63, v4
	v_cndmask_b32_e32 v5, v5, v4, vcc
	v_sub_u32_e32 v4, 62, v4
	v_or_b32_e32 v13, 5, v11
	v_add_u32_e32 v5, s7, v5
	v_cndmask_b32_e32 v4, v4, v13, vcc
	v_add_u32_e32 v13, s7, v4
	v_mad_i64_i32 v[4:5], s[14:15], v5, s88, v[2:3]
	v_lshl_add_u64 v[4:5], v[4:5], 0, s[24:25]
	v_lshl_add_u64 v[4:5], v[4:5], 0, v[0:1]
	global_load_ushort v25, v[4:5], off offset:1024
	v_mad_i64_i32 v[4:5], s[14:15], v13, s88, v[2:3]
	v_lshl_add_u64 v[4:5], v[4:5], 0, s[24:25]
	v_lshl_add_u64 v[4:5], v[4:5], 0, v[0:1]
	global_load_ushort v13, v[4:5], off offset:1024
	v_or_b32_e32 v4, 6, v11
	v_sub_u32_e32 v5, 63, v4
	v_cndmask_b32_e32 v5, v5, v4, vcc
	v_sub_u32_e32 v4, 62, v4
	v_or_b32_e32 v26, 7, v11
	v_add_u32_e32 v5, s7, v5
	v_cndmask_b32_e32 v4, v4, v26, vcc
	v_add_u32_e32 v26, s7, v4
	v_mad_i64_i32 v[4:5], s[14:15], v5, s88, v[2:3]
	v_lshl_add_u64 v[4:5], v[4:5], 0, s[24:25]
	v_lshl_add_u64 v[4:5], v[4:5], 0, v[0:1]
	global_load_ushort v27, v[4:5], off offset:1024
	v_mad_i64_i32 v[4:5], s[14:15], v26, s88, v[2:3]
	v_lshl_add_u64 v[4:5], v[4:5], 0, s[24:25]
	v_lshl_add_u64 v[4:5], v[4:5], 0, v[0:1]
	global_load_ushort v26, v[4:5], off offset:1024
	v_or_b32_e32 v4, 8, v11
	v_sub_u32_e32 v5, 63, v4
	v_cndmask_b32_e32 v5, v5, v4, vcc
	v_sub_u32_e32 v4, 62, v4
	v_or_b32_e32 v28, 9, v11
	v_add_u32_e32 v5, s7, v5
	v_cndmask_b32_e32 v4, v4, v28, vcc
	v_add_u32_e32 v28, s7, v4
	v_mad_i64_i32 v[4:5], s[14:15], v5, s88, v[2:3]
	v_lshl_add_u64 v[4:5], v[4:5], 0, s[24:25]
	v_lshl_add_u64 v[4:5], v[4:5], 0, v[0:1]
	global_load_ushort v29, v[4:5], off offset:1024
	v_mad_i64_i32 v[4:5], s[14:15], v28, s88, v[2:3]
	v_lshl_add_u64 v[4:5], v[4:5], 0, s[24:25]
	v_lshl_add_u64 v[4:5], v[4:5], 0, v[0:1]
	global_load_ushort v28, v[4:5], off offset:1024
	v_or_b32_e32 v4, 10, v11
	v_sub_u32_e32 v5, 63, v4
	v_cndmask_b32_e32 v5, v5, v4, vcc
	v_sub_u32_e32 v4, 62, v4
	v_or_b32_e32 v30, 11, v11
	v_add_u32_e32 v5, s7, v5
	v_cndmask_b32_e32 v4, v4, v30, vcc
	v_add_u32_e32 v30, s7, v4
	v_mad_i64_i32 v[4:5], s[14:15], v5, s88, v[2:3]
	v_lshl_add_u64 v[4:5], v[4:5], 0, s[24:25]
	v_lshl_add_u64 v[4:5], v[4:5], 0, v[0:1]
	global_load_ushort v31, v[4:5], off offset:1024
	v_mad_i64_i32 v[4:5], s[14:15], v30, s88, v[2:3]
	v_lshl_add_u64 v[4:5], v[4:5], 0, s[24:25]
	v_lshl_add_u64 v[4:5], v[4:5], 0, v[0:1]
	global_load_ushort v30, v[4:5], off offset:1024
	v_or_b32_e32 v4, 12, v11
	v_sub_u32_e32 v5, 63, v4
	v_cndmask_b32_e32 v5, v5, v4, vcc
	v_sub_u32_e32 v4, 62, v4
	v_or_b32_e32 v32, 13, v11
	v_add_u32_e32 v5, s7, v5
	v_cndmask_b32_e32 v4, v4, v32, vcc
	v_add_u32_e32 v32, s7, v4
	v_mad_i64_i32 v[4:5], s[14:15], v5, s88, v[2:3]
	v_lshl_add_u64 v[4:5], v[4:5], 0, s[24:25]
	v_lshl_add_u64 v[4:5], v[4:5], 0, v[0:1]
	global_load_ushort v33, v[4:5], off offset:1024
	v_mad_i64_i32 v[4:5], s[14:15], v32, s88, v[2:3]
	v_lshl_add_u64 v[4:5], v[4:5], 0, s[24:25]
	v_lshl_add_u64 v[4:5], v[4:5], 0, v[0:1]
	global_load_ushort v32, v[4:5], off offset:1024
	v_or_b32_e32 v4, 14, v11
	v_sub_u32_e32 v5, 63, v4
	v_cndmask_b32_e32 v5, v5, v4, vcc
	v_sub_u32_e32 v4, 62, v4
	v_or_b32_e32 v6, 15, v6
	v_cndmask_b32_e32 v4, v4, v6, vcc
	v_add_u32_e32 v5, s7, v5
	v_add_u32_e32 v6, s7, v4
	v_mad_i64_i32 v[4:5], s[14:15], v5, s88, v[2:3]
	v_mad_i64_i32 v[2:3], s[14:15], v6, s88, v[2:3]
	v_lshl_add_u64 v[4:5], v[4:5], 0, s[24:25]
	v_lshl_add_u64 v[2:3], v[2:3], 0, s[24:25]
	v_lshl_add_u64 v[4:5], v[4:5], 0, v[0:1]
	v_lshl_add_u64 v[2:3], v[2:3], 0, v[0:1]
	global_load_ushort v34, v[4:5], off offset:1024
	global_load_ushort v0, v[2:3], off offset:1024
	s_waitcnt vmcnt(12)
	v_lshl_or_b32 v3, v9, 16, v12
	v_lshl_or_b32 v2, v7, 16, v8
	s_waitcnt vmcnt(10)
	v_lshl_or_b32 v4, v13, 16, v25
	s_movk_i32 s4, 0x400
	s_waitcnt vmcnt(8)
	v_lshl_or_b32 v5, v26, 16, v27
	s_waitcnt vmcnt(6)
	v_lshl_or_b32 v6, v28, 16, v29
	s_waitcnt vmcnt(4)
	v_lshl_or_b32 v7, v30, 16, v31
	s_waitcnt vmcnt(2)
	v_lshl_or_b32 v8, v32, 16, v33
	s_waitcnt vmcnt(0)
	v_lshl_or_b32 v9, v0, 16, v34
	v_mul_u32_u24_e32 v0, 0x90, v10
	v_lshlrev_b32_e32 v10, 1, v11
	v_add3_u32 v0, 0, v0, v10
	ds_write_b128 v0, v[2:5] offset:9216
	ds_write_b128 v0, v[6:9] offset:9232
	v_mov_b32_e32 v2, v202
	s_nop 0
	v_cmp_gt_i32_e64 s[40:41], s4, v2
	s_and_saveexec_b64 s[24:25], s[40:41]
	s_cbranch_execz .LBB0_675
	s_lshl_b32 s4, s10, 6
	v_readlane_b32 s10, v253, 54
	v_readlane_b32 s11, v253, 55
	s_add_u32 s10, s10, s4
	v_and_b32_e32 v0, 15, v2
	s_addc_u32 s11, s11, 0
	v_lshlrev_b32_e32 v0, 2, v0
	v_lshl_add_u64 v[4:5], s[10:11], 0, v[0:1]
	v_max_i32_e32 v0, 0x200, v2
	v_sub_u32_e32 v0, v0, v2
	v_add_u32_e32 v0, 0x1ff, v0
	v_cmp_lt_u32_e64 s[40:41], s89, v0
	s_mov_b64 s[14:15], -1
	v_mov_b32_e32 v3, v2
	s_and_saveexec_b64 s[20:21], s[40:41]
	s_cbranch_execz .LBB0_672
	v_lshrrev_b32_e32 v0, 9, v0
	v_add_u32_e32 v0, 1, v0
	v_and_b32_e32 v8, 0xfffffe, v0
	v_add_u32_e32 v3, 0x200, v2
	s_add_i32 s4, 0, 0x6c00
	s_mov_b32 s10, s7
	v_lshl_add_u32 v9, v2, 2, s4
	s_mov_b64 s[14:15], 0
	v_mov_b32_e32 v10, v8
	v_mov_b64_e32 v[6:7], v[2:3]
